# meta_reduce: 17 loads per 256-col group issued together with counted vmcnt ladder instead of 68 serialized round trips (same summation order)
# baseline (speedup 1.0000x reference)
; __device__ __forceinline__ unsigned cvtpk(float lo, float hi) { f32x2 v = {lo, hi}; bf16x2_t b = __builtin_convertvector(v, bf16x2_t); return __builtin_bit_cast(unsigned, b); }
; __device__ __forceinline__ void meta_reduce(const float* PART, float* metah, bf16_t* P, u64* rowss_next, int gw, int NGW, int lane) {
;     for (int lrow = gw; lrow < MREAL - ROWS_MAIN; lrow += NGW) {
;         float ss = 0.f;
; #pragma unroll
;         for (int k = 0; k < 4; ++k) {
;             const int col = k * 256 + lane * 4;
;             f32x4 sum = *(const f32x4*)(metah + (size_t)lrow * DM + col);
; #pragma unroll
;             for (int ks = 0; ks < DOWN_KS; ++ks) sum += *(const f32x4*)(PART + ((size_t)ks * 512 + lrow) * DM + col);
;             *(f32x4*)(metah + (size_t)lrow * DM + col) = sum;
;             if (P) { u32x2 pk; pk.x = cvtpk(sum[0], sum[1]); pk.y = cvtpk(sum[2], sum[3]); *(u32x2*)(P + (size_t)(ROWS_MAIN + lrow) * DM + col) = pk; }
.LBB0_2324:
	v_lshl_add_u64 v[12:13], s[6:7], 0, v[20:21]
	s_waitcnt lgkmcnt(0)
	v_add_u32_e32 v0, 0x18000, v17
	v_ashrrev_i32_e32 v1, 31, v0
	v_lshlrev_b64 v[0:1], 11, v[0:1]
	v_lshl_add_u64 v[22:23], s[8:9], 0, v[0:1]
	v_lshlrev_b32_e32 v32, 1, v16
	v_lshl_add_u64 v[22:23], v[22:23], 0, v[32:33]
	s_mov_b32 s44, 0x800000
	s_mov_b32 s45, 0
	v_lshl_add_u64 v[24:25], v[12:13], 0, s[44:45]
	s_mov_b32 s44, 0x31a00000
	v_lshl_add_u64 v[104:105], v[12:13], 0, s[44:45]
	s_mov_b32 s44, 0x200000
	v_lshl_add_u64 v[106:107], v[104:105], 0, s[44:45]
	v_lshl_add_u64 v[108:109], v[106:107], 0, s[44:45]
	v_lshl_add_u64 v[110:111], v[108:109], 0, s[44:45]
	v_lshl_add_u64 v[112:113], v[110:111], 0, s[44:45]
	v_lshl_add_u64 v[114:115], v[112:113], 0, s[44:45]
	v_lshl_add_u64 v[116:117], v[114:115], 0, s[44:45]
	v_lshl_add_u64 v[118:119], v[116:117], 0, s[44:45]
	v_lshl_add_u64 v[120:121], v[118:119], 0, s[44:45]
	v_lshl_add_u64 v[122:123], v[120:121], 0, s[44:45]
	v_lshl_add_u64 v[124:125], v[122:123], 0, s[44:45]
	v_lshl_add_u64 v[126:127], v[124:125], 0, s[44:45]
	v_lshl_add_u64 v[128:129], v[126:127], 0, s[44:45]
	v_lshl_add_u64 v[130:131], v[128:129], 0, s[44:45]
	v_lshl_add_u64 v[132:133], v[130:131], 0, s[44:45]
	v_lshl_add_u64 v[134:135], v[132:133], 0, s[44:45]
	global_load_dwordx4 v[36:39], v[24:25], off
	global_load_dwordx4 v[40:43], v[104:105], off
	global_load_dwordx4 v[44:47], v[106:107], off
	global_load_dwordx4 v[48:51], v[108:109], off
	global_load_dwordx4 v[52:55], v[110:111], off
	global_load_dwordx4 v[56:59], v[112:113], off
	global_load_dwordx4 v[60:63], v[114:115], off
	global_load_dwordx4 v[64:67], v[116:117], off
	global_load_dwordx4 v[68:71], v[118:119], off
	global_load_dwordx4 v[72:75], v[120:121], off
	global_load_dwordx4 v[76:79], v[122:123], off
	global_load_dwordx4 v[80:83], v[124:125], off
	global_load_dwordx4 v[84:87], v[126:127], off
	global_load_dwordx4 v[88:91], v[128:129], off
	global_load_dwordx4 v[92:95], v[130:131], off
	global_load_dwordx4 v[96:99], v[132:133], off
	global_load_dwordx4 v[100:103], v[134:135], off
	s_waitcnt vmcnt(15)
	v_pk_add_f32 v[0:1], v[36:37], v[40:41]
	v_pk_add_f32 v[2:3], v[38:39], v[42:43]
	s_waitcnt vmcnt(14)
	v_pk_add_f32 v[0:1], v[0:1], v[44:45]
	v_pk_add_f32 v[2:3], v[2:3], v[46:47]
	s_waitcnt vmcnt(13)
	v_pk_add_f32 v[0:1], v[0:1], v[48:49]
	v_pk_add_f32 v[2:3], v[2:3], v[50:51]
	s_waitcnt vmcnt(12)
	v_pk_add_f32 v[0:1], v[0:1], v[52:53]
	v_pk_add_f32 v[2:3], v[2:3], v[54:55]
	s_waitcnt vmcnt(11)
	v_pk_add_f32 v[0:1], v[0:1], v[56:57]
	v_pk_add_f32 v[2:3], v[2:3], v[58:59]
	s_waitcnt vmcnt(10)
	v_pk_add_f32 v[0:1], v[0:1], v[60:61]
	v_pk_add_f32 v[2:3], v[2:3], v[62:63]
	s_waitcnt vmcnt(9)
	v_pk_add_f32 v[0:1], v[0:1], v[64:65]
	v_pk_add_f32 v[2:3], v[2:3], v[66:67]
	s_waitcnt vmcnt(8)
	v_pk_add_f32 v[0:1], v[0:1], v[68:69]
	v_pk_add_f32 v[2:3], v[2:3], v[70:71]
	s_waitcnt vmcnt(7)
	v_pk_add_f32 v[0:1], v[0:1], v[72:73]
	v_pk_add_f32 v[2:3], v[2:3], v[74:75]
	s_waitcnt vmcnt(6)
	v_pk_add_f32 v[0:1], v[0:1], v[76:77]
	v_pk_add_f32 v[2:3], v[2:3], v[78:79]
	s_waitcnt vmcnt(5)
	v_pk_add_f32 v[0:1], v[0:1], v[80:81]
	v_pk_add_f32 v[2:3], v[2:3], v[82:83]
	s_waitcnt vmcnt(4)
	v_pk_add_f32 v[0:1], v[0:1], v[84:85]
	v_pk_add_f32 v[2:3], v[2:3], v[86:87]
	s_waitcnt vmcnt(3)
	v_pk_add_f32 v[0:1], v[0:1], v[88:89]
	v_pk_add_f32 v[2:3], v[2:3], v[90:91]
	s_waitcnt vmcnt(2)
	v_pk_add_f32 v[0:1], v[0:1], v[92:93]
	v_pk_add_f32 v[2:3], v[2:3], v[94:95]
	s_waitcnt vmcnt(1)
	v_pk_add_f32 v[0:1], v[0:1], v[96:97]
	v_pk_add_f32 v[2:3], v[2:3], v[98:99]
	s_waitcnt vmcnt(0)
	v_pk_add_f32 v[0:1], v[0:1], v[100:101]
	v_pk_add_f32 v[2:3], v[2:3], v[102:103]
	global_store_dwordx4 v[24:25], v[0:3], off
	s_cmp_lg_u64 s[18:19], 0
	s_cbranch_scc0 .Lmr_skipP_0
	v_cvt_pk_bf16_f32 v34, v0, v1
	v_cvt_pk_bf16_f32 v35, v2, v3
	global_store_dwordx2 v[22:23], v[34:35], off
.Lmr_skipP_0:
	global_load_dwordx4 v[36:39], v[24:25], off offset:1024
	global_load_dwordx4 v[40:43], v[104:105], off offset:1024
	global_load_dwordx4 v[44:47], v[106:107], off offset:1024
	global_load_dwordx4 v[48:51], v[108:109], off offset:1024
	global_load_dwordx4 v[52:55], v[110:111], off offset:1024
	global_load_dwordx4 v[56:59], v[112:113], off offset:1024
	global_load_dwordx4 v[60:63], v[114:115], off offset:1024
	global_load_dwordx4 v[64:67], v[116:117], off offset:1024
	global_load_dwordx4 v[68:71], v[118:119], off offset:1024
	global_load_dwordx4 v[72:75], v[120:121], off offset:1024
	global_load_dwordx4 v[76:79], v[122:123], off offset:1024
	global_load_dwordx4 v[80:83], v[124:125], off offset:1024
	global_load_dwordx4 v[84:87], v[126:127], off offset:1024
	global_load_dwordx4 v[88:91], v[128:129], off offset:1024
	global_load_dwordx4 v[92:95], v[130:131], off offset:1024
	global_load_dwordx4 v[96:99], v[132:133], off offset:1024
	global_load_dwordx4 v[100:103], v[134:135], off offset:1024
	s_waitcnt vmcnt(15)
	v_pk_add_f32 v[4:5], v[36:37], v[40:41]
	v_pk_add_f32 v[6:7], v[38:39], v[42:43]
	s_waitcnt vmcnt(14)
	v_pk_add_f32 v[4:5], v[4:5], v[44:45]
	v_pk_add_f32 v[6:7], v[6:7], v[46:47]
	s_waitcnt vmcnt(13)
	v_pk_add_f32 v[4:5], v[4:5], v[48:49]
	v_pk_add_f32 v[6:7], v[6:7], v[50:51]
	s_waitcnt vmcnt(12)
	v_pk_add_f32 v[4:5], v[4:5], v[52:53]
	v_pk_add_f32 v[6:7], v[6:7], v[54:55]
	s_waitcnt vmcnt(11)
	v_pk_add_f32 v[4:5], v[4:5], v[56:57]
	v_pk_add_f32 v[6:7], v[6:7], v[58:59]
	s_waitcnt vmcnt(10)
	v_pk_add_f32 v[4:5], v[4:5], v[60:61]
	v_pk_add_f32 v[6:7], v[6:7], v[62:63]
	s_waitcnt vmcnt(9)
	v_pk_add_f32 v[4:5], v[4:5], v[64:65]
	v_pk_add_f32 v[6:7], v[6:7], v[66:67]
	s_waitcnt vmcnt(8)
	v_pk_add_f32 v[4:5], v[4:5], v[68:69]
	v_pk_add_f32 v[6:7], v[6:7], v[70:71]
	s_waitcnt vmcnt(7)
	v_pk_add_f32 v[4:5], v[4:5], v[72:73]
	v_pk_add_f32 v[6:7], v[6:7], v[74:75]
	s_waitcnt vmcnt(6)
	v_pk_add_f32 v[4:5], v[4:5], v[76:77]
	v_pk_add_f32 v[6:7], v[6:7], v[78:79]
	s_waitcnt vmcnt(5)
	v_pk_add_f32 v[4:5], v[4:5], v[80:81]
	v_pk_add_f32 v[6:7], v[6:7], v[82:83]
	s_waitcnt vmcnt(4)
	v_pk_add_f32 v[4:5], v[4:5], v[84:85]
	v_pk_add_f32 v[6:7], v[6:7], v[86:87]
	s_waitcnt vmcnt(3)
	v_pk_add_f32 v[4:5], v[4:5], v[88:89]
	v_pk_add_f32 v[6:7], v[6:7], v[90:91]
	s_waitcnt vmcnt(2)
	v_pk_add_f32 v[4:5], v[4:5], v[92:93]
	v_pk_add_f32 v[6:7], v[6:7], v[94:95]
	s_waitcnt vmcnt(1)
	v_pk_add_f32 v[4:5], v[4:5], v[96:97]
	v_pk_add_f32 v[6:7], v[6:7], v[98:99]
	s_waitcnt vmcnt(0)
	v_pk_add_f32 v[4:5], v[4:5], v[100:101]
	v_pk_add_f32 v[6:7], v[6:7], v[102:103]
	global_store_dwordx4 v[24:25], v[4:7], off offset:1024
	s_cmp_lg_u64 s[18:19], 0
	s_cbranch_scc0 .Lmr_skipP_1
	v_cvt_pk_bf16_f32 v34, v4, v5
	v_cvt_pk_bf16_f32 v35, v6, v7
	global_store_dwordx2 v[22:23], v[34:35], off offset:512
; __device__ __forceinline__ unsigned cvtpk(float lo, float hi) { f32x2 v = {lo, hi}; bf16x2_t b = __builtin_convertvector(v, bf16x2_t); return __builtin_bit_cast(unsigned, b); }
; __device__ __forceinline__ void meta_reduce(const float* PART, float* metah, bf16_t* P, u64* rowss_next, int gw, int NGW, int lane) {
;     ...
;         for (int k = 0; k < 4; ++k) {
;             const int col = k * 256 + lane * 4;
;             f32x4 sum = *(const f32x4*)(metah + (size_t)lrow * DM + col);
; #pragma unroll
;             for (int ks = 0; ks < DOWN_KS; ++ks) sum += *(const f32x4*)(PART + ((size_t)ks * 512 + lrow) * DM + col);
;             *(f32x4*)(metah + (size_t)lrow * DM + col) = sum;
;             if (P) { u32x2 pk; pk.x = cvtpk(sum[0], sum[1]); pk.y = cvtpk(sum[2], sum[3]); *(u32x2*)(P + (size_t)(ROWS_MAIN + lrow) * DM + col) = pk; }
.Lmr_skipP_1:
	global_load_dwordx4 v[36:39], v[24:25], off offset:2048
	global_load_dwordx4 v[40:43], v[104:105], off offset:2048
	global_load_dwordx4 v[44:47], v[106:107], off offset:2048
	global_load_dwordx4 v[48:51], v[108:109], off offset:2048
	global_load_dwordx4 v[52:55], v[110:111], off offset:2048
	global_load_dwordx4 v[56:59], v[112:113], off offset:2048
	global_load_dwordx4 v[60:63], v[114:115], off offset:2048
	global_load_dwordx4 v[64:67], v[116:117], off offset:2048
	global_load_dwordx4 v[68:71], v[118:119], off offset:2048
	global_load_dwordx4 v[72:75], v[120:121], off offset:2048
	global_load_dwordx4 v[76:79], v[122:123], off offset:2048
	global_load_dwordx4 v[80:83], v[124:125], off offset:2048
	global_load_dwordx4 v[84:87], v[126:127], off offset:2048
	global_load_dwordx4 v[88:91], v[128:129], off offset:2048
	global_load_dwordx4 v[92:95], v[130:131], off offset:2048
	global_load_dwordx4 v[96:99], v[132:133], off offset:2048
	global_load_dwordx4 v[100:103], v[134:135], off offset:2048
	s_waitcnt vmcnt(15)
	v_pk_add_f32 v[8:9], v[36:37], v[40:41]
	v_pk_add_f32 v[10:11], v[38:39], v[42:43]
	s_waitcnt vmcnt(14)
	v_pk_add_f32 v[8:9], v[8:9], v[44:45]
	v_pk_add_f32 v[10:11], v[10:11], v[46:47]
	s_waitcnt vmcnt(13)
	v_pk_add_f32 v[8:9], v[8:9], v[48:49]
	v_pk_add_f32 v[10:11], v[10:11], v[50:51]
	s_waitcnt vmcnt(12)
	v_pk_add_f32 v[8:9], v[8:9], v[52:53]
	v_pk_add_f32 v[10:11], v[10:11], v[54:55]
	s_waitcnt vmcnt(11)
	v_pk_add_f32 v[8:9], v[8:9], v[56:57]
	v_pk_add_f32 v[10:11], v[10:11], v[58:59]
	s_waitcnt vmcnt(10)
	v_pk_add_f32 v[8:9], v[8:9], v[60:61]
	v_pk_add_f32 v[10:11], v[10:11], v[62:63]
	s_waitcnt vmcnt(9)
	v_pk_add_f32 v[8:9], v[8:9], v[64:65]
	v_pk_add_f32 v[10:11], v[10:11], v[66:67]
	s_waitcnt vmcnt(8)
	v_pk_add_f32 v[8:9], v[8:9], v[68:69]
	v_pk_add_f32 v[10:11], v[10:11], v[70:71]
	s_waitcnt vmcnt(7)
	v_pk_add_f32 v[8:9], v[8:9], v[72:73]
	v_pk_add_f32 v[10:11], v[10:11], v[74:75]
	s_waitcnt vmcnt(6)
	v_pk_add_f32 v[8:9], v[8:9], v[76:77]
	v_pk_add_f32 v[10:11], v[10:11], v[78:79]
	s_waitcnt vmcnt(5)
	v_pk_add_f32 v[8:9], v[8:9], v[80:81]
	v_pk_add_f32 v[10:11], v[10:11], v[82:83]
	s_waitcnt vmcnt(4)
	v_pk_add_f32 v[8:9], v[8:9], v[84:85]
	v_pk_add_f32 v[10:11], v[10:11], v[86:87]
	s_waitcnt vmcnt(3)
	v_pk_add_f32 v[8:9], v[8:9], v[88:89]
	v_pk_add_f32 v[10:11], v[10:11], v[90:91]
	s_waitcnt vmcnt(2)
	v_pk_add_f32 v[8:9], v[8:9], v[92:93]
	v_pk_add_f32 v[10:11], v[10:11], v[94:95]
	s_waitcnt vmcnt(1)
	v_pk_add_f32 v[8:9], v[8:9], v[96:97]
	v_pk_add_f32 v[10:11], v[10:11], v[98:99]
	s_waitcnt vmcnt(0)
	v_pk_add_f32 v[8:9], v[8:9], v[100:101]
	v_pk_add_f32 v[10:11], v[10:11], v[102:103]
	global_store_dwordx4 v[24:25], v[8:11], off offset:2048
	s_cmp_lg_u64 s[18:19], 0
	s_cbranch_scc0 .Lmr_skipP_2
	v_cvt_pk_bf16_f32 v34, v8, v9
	v_cvt_pk_bf16_f32 v35, v10, v11
	global_store_dwordx2 v[22:23], v[34:35], off offset:1024
; __device__ __forceinline__ unsigned cvtpk(float lo, float hi) { f32x2 v = {lo, hi}; bf16x2_t b = __builtin_convertvector(v, bf16x2_t); return __builtin_bit_cast(unsigned, b); }
; __device__ __forceinline__ void meta_reduce(const float* PART, float* metah, bf16_t* P, u64* rowss_next, int gw, int NGW, int lane) {
;     ...
;         for (int k = 0; k < 4; ++k) {
;             const int col = k * 256 + lane * 4;
;             f32x4 sum = *(const f32x4*)(metah + (size_t)lrow * DM + col);
; #pragma unroll
;             for (int ks = 0; ks < DOWN_KS; ++ks) sum += *(const f32x4*)(PART + ((size_t)ks * 512 + lrow) * DM + col);
;             *(f32x4*)(metah + (size_t)lrow * DM + col) = sum;
;             if (P) { u32x2 pk; pk.x = cvtpk(sum[0], sum[1]); pk.y = cvtpk(sum[2], sum[3]); *(u32x2*)(P + (size_t)(ROWS_MAIN + lrow) * DM + col) = pk; }
;             ss += (sum[0] * sum[0] + sum[1] * sum[1]) + (sum[2] * sum[2] + sum[3] * sum[3]);
;         }
;         ss = wave_sum(ss);
;         if (lane == 0 && rowss_next) rowss_next[ROWS_MAIN + lrow] = (u64)(ss * SS_SCALE);
.Lmr_skipP_2:
	global_load_dwordx4 v[36:39], v[24:25], off offset:3072
	global_load_dwordx4 v[40:43], v[104:105], off offset:3072
	global_load_dwordx4 v[44:47], v[106:107], off offset:3072
	global_load_dwordx4 v[48:51], v[108:109], off offset:3072
	global_load_dwordx4 v[52:55], v[110:111], off offset:3072
	global_load_dwordx4 v[56:59], v[112:113], off offset:3072
	global_load_dwordx4 v[60:63], v[114:115], off offset:3072
	global_load_dwordx4 v[64:67], v[116:117], off offset:3072
	global_load_dwordx4 v[68:71], v[118:119], off offset:3072
	global_load_dwordx4 v[72:75], v[120:121], off offset:3072
	global_load_dwordx4 v[76:79], v[122:123], off offset:3072
	global_load_dwordx4 v[80:83], v[124:125], off offset:3072
	global_load_dwordx4 v[84:87], v[126:127], off offset:3072
	global_load_dwordx4 v[88:91], v[128:129], off offset:3072
	global_load_dwordx4 v[92:95], v[130:131], off offset:3072
	global_load_dwordx4 v[96:99], v[132:133], off offset:3072
	global_load_dwordx4 v[100:103], v[134:135], off offset:3072
	s_waitcnt vmcnt(15)
	v_pk_add_f32 v[12:13], v[36:37], v[40:41]
	v_pk_add_f32 v[14:15], v[38:39], v[42:43]
	s_waitcnt vmcnt(14)
	v_pk_add_f32 v[12:13], v[12:13], v[44:45]
	v_pk_add_f32 v[14:15], v[14:15], v[46:47]
	s_waitcnt vmcnt(13)
	v_pk_add_f32 v[12:13], v[12:13], v[48:49]
	v_pk_add_f32 v[14:15], v[14:15], v[50:51]
	s_waitcnt vmcnt(12)
	v_pk_add_f32 v[12:13], v[12:13], v[52:53]
	v_pk_add_f32 v[14:15], v[14:15], v[54:55]
	s_waitcnt vmcnt(11)
	v_pk_add_f32 v[12:13], v[12:13], v[56:57]
	v_pk_add_f32 v[14:15], v[14:15], v[58:59]
	s_waitcnt vmcnt(10)
	v_pk_add_f32 v[12:13], v[12:13], v[60:61]
	v_pk_add_f32 v[14:15], v[14:15], v[62:63]
	s_waitcnt vmcnt(9)
	v_pk_add_f32 v[12:13], v[12:13], v[64:65]
	v_pk_add_f32 v[14:15], v[14:15], v[66:67]
	s_waitcnt vmcnt(8)
	v_pk_add_f32 v[12:13], v[12:13], v[68:69]
	v_pk_add_f32 v[14:15], v[14:15], v[70:71]
	s_waitcnt vmcnt(7)
	v_pk_add_f32 v[12:13], v[12:13], v[72:73]
	v_pk_add_f32 v[14:15], v[14:15], v[74:75]
	s_waitcnt vmcnt(6)
	v_pk_add_f32 v[12:13], v[12:13], v[76:77]
	v_pk_add_f32 v[14:15], v[14:15], v[78:79]
	s_waitcnt vmcnt(5)
	v_pk_add_f32 v[12:13], v[12:13], v[80:81]
	v_pk_add_f32 v[14:15], v[14:15], v[82:83]
	s_waitcnt vmcnt(4)
	v_pk_add_f32 v[12:13], v[12:13], v[84:85]
	v_pk_add_f32 v[14:15], v[14:15], v[86:87]
	s_waitcnt vmcnt(3)
	v_pk_add_f32 v[12:13], v[12:13], v[88:89]
	v_pk_add_f32 v[14:15], v[14:15], v[90:91]
	s_waitcnt vmcnt(2)
	v_pk_add_f32 v[12:13], v[12:13], v[92:93]
	v_pk_add_f32 v[14:15], v[14:15], v[94:95]
	s_waitcnt vmcnt(1)
	v_pk_add_f32 v[12:13], v[12:13], v[96:97]
	v_pk_add_f32 v[14:15], v[14:15], v[98:99]
	s_waitcnt vmcnt(0)
	v_pk_add_f32 v[12:13], v[12:13], v[100:101]
	v_pk_add_f32 v[14:15], v[14:15], v[102:103]
	global_store_dwordx4 v[24:25], v[12:15], off offset:3072
	s_cmp_lg_u64 s[18:19], 0
	s_cbranch_scc0 .Lmr_skipP_3
	v_cvt_pk_bf16_f32 v34, v12, v13
	v_cvt_pk_bf16_f32 v35, v14, v15
	global_store_dwordx2 v[22:23], v[34:35], off offset:1536
.Lmr_skipP_3:
.LBB0_2332:
	v_mul_f32_e32 v1, v1, v1
	v_fmac_f32_e32 v1, v0, v0
	v_mul_f32_e32 v0, v3, v3
	v_fmac_f32_e32 v0, v2, v2
	v_add_f32_e32 v0, v1, v0
	v_mul_f32_e32 v1, v5, v5
	v_mul_f32_e32 v2, v7, v7
	v_fmac_f32_e32 v1, v4, v4
	v_fmac_f32_e32 v2, v6, v6
	v_add_f32_e32 v1, v1, v2
	v_add_f32_e32 v0, v0, v1
	v_mul_f32_e32 v1, v9, v9
	v_mul_f32_e32 v2, v11, v11
	v_fmac_f32_e32 v1, v8, v8
	v_fmac_f32_e32 v2, v10, v10
	v_add_f32_e32 v1, v1, v2
	v_add_f32_e32 v0, v0, v1
	v_mul_f32_e32 v1, v13, v13
	v_mul_f32_e32 v2, v15, v15
	v_fmac_f32_e32 v1, v12, v12
	v_fmac_f32_e32 v2, v14, v14
	v_add_f32_e32 v1, v1, v2
	v_add_f32_e32 v0, v0, v1
	ds_bpermute_b32 v1, v26, v0
	s_waitcnt lgkmcnt(0)
	v_add_f32_e32 v0, v0, v1
	ds_bpermute_b32 v1, v27, v0
	s_waitcnt lgkmcnt(0)
	v_add_f32_e32 v0, v0, v1
	ds_bpermute_b32 v1, v28, v0
	s_waitcnt lgkmcnt(0)
	v_add_f32_e32 v0, v0, v1
	ds_bpermute_b32 v1, v29, v0
	s_waitcnt lgkmcnt(0)
	v_add_f32_e32 v0, v0, v1
	ds_bpermute_b32 v1, v30, v0
	s_waitcnt lgkmcnt(0)
	v_add_f32_e32 v0, v0, v1
	ds_bpermute_b32 v1, v31, v0
	s_and_saveexec_b64 s[2:3], s[14:15]
	s_cbranch_execz .LBB0_2323
	s_waitcnt lgkmcnt(0)
	v_add_f32_e32 v0, v0, v1
	v_mul_f32_e32 v0, 0x49800000, v0
	v_trunc_f32_e32 v0, v0
	v_mul_f32_e32 v1, 0x2f800000, v0
	v_floor_f32_e32 v1, v1
	v_fmac_f32_e32 v0, 0xcf800000, v1
	v_cvt_u32_f32_e32 v0, v0
	v_cvt_u32_f32_e32 v1, v1
	v_lshl_add_u64 v[2:3], s[6:7], 0, v[18:19]
	global_store_dwordx2 v[2:3], v[0:1], off
	s_branch .LBB0_2323
